# work queue: wait for the prefetched index with vmcnt(4) (only the oldest op, the atomic, is needed; the item's last four row stores stay in flight); stacked on stack24
# baseline (speedup 1.0000x reference)
; __device__ __forceinline__ int launder_v(int v) { asm volatile("" : "+v"(v)); return v; }
; __device__ __forceinline__ const float* arg_in(int k) { const int o = launder_s(k * 8); return *(const float* const*)((const char*)__builtin_amdgcn_kernarg_segment_ptr() + o); }
; #define ws (arg_ws())
; __global__ void __launch_bounds__(NTHR, 2) mk_fwd(Args a) {
;     ...
;                     if (useq) { idx = (int)qw[it & 1]; if (idx >= 160) break; bsel = xg; if (tid == 0) nxt = __hip_atomic_fetch_add(qcnt, 1u, __ATOMIC_RELAXED, __HIP_MEMORY_SCOPE_AGENT); }
;                     else { if (sidx >= BATCH * 160) break; bsel = sidx / 160; idx = sidx % 160; sidx += G; }
;                     const int cls = idx >> 4, e = idx & 15;
;                     if (cls >= 8) {
;                         const int r = bsel * 32 + (idx - 128);
;                         poolconv_rows(proj + (size_t)bsel * BPAD, mix, (const bf16_t*)(ws + WS_WPT) + (size_t)l * 4 * 4096, arg_in(12) + l * 256, arg_in(13) + l * 768, r * 128, ldsl, launder_v(tid));
;                     } else {
;                         const int hsel = 7 - cls;
;                         const int qb = (e & 1) ? 8 + (e >> 1) : 7 - (e >> 1);
;                         att::attn_unit<20, ATT_SKIP_T>(bsel, hsel, qb, proj + (size_t)bsel * BPAD, mix, arg_in(10) + l * 512 + hsel * 64, lam, 1.f - lambda_init, kn2, (char*)lds);
;                     }
;                     if (useq && tid == 0) qw[(it + 1) & 1] = nxt;
.LBB0_407:
	s_mov_b64 s[36:37], exec
	v_readlane_b32 s14, v253, 58
	v_readlane_b32 s15, v253, 59
	s_and_b64 s[14:15], s[36:37], s[14:15]
	s_mov_b64 exec, s[14:15]
	s_cbranch_execz .LBB0_294
	s_andn2_b32 s14, 1, s88
	s_lshl_b32 s14, s14, 2
	s_add_i32 s14, s14, 0
	s_add_i32 s14, s14, 0x22040
	v_mov_b32_e32 v0, s14
	s_waitcnt vmcnt(4)
	ds_write_b32 v0, v166
	s_branch .LBB0_294
